# mixer B: next item's Q (LDS DMA) and first K/V tile requested from the epilogue; next prologue skips its loads
# baseline (speedup 1.0000x reference)
; #define LAS __attribute__((address_space(3)))
; DI size_t zrowU(int row0, int NT) { return ((size_t)((row0 >> 8) * NT) << 16) + (size_t)((((row0 >> 7) & 1) << 15) | (((row0 >> 5) & 1) << 14) | (((row0 >> 6) & 1) << 11)); }
; DI unsigned zlaneRC(int r5, int col) { return (unsigned)(((col >> 8) << 16) | ((r5 >> 4) << 13) | (((col >> 7) & 1) << 12) | (((col >> 5) & 3) << 9) | (((col >> 3) & 3) << 7) | ((r5 & 15) << 3) | (col & 7)); }
; DI void attnB_item(bf16_t* z, int hh, int qs, LAS bf16_t* vs, int lane) {
;     const int c = lane & 31, h = lane >> 5;
;     const bool metaq = qs < 0;
;     const int qrow = metaq ? SEQ + c : 32 * qs + c;
;     const int qpos = metaq ? (c < NMETA ? c : 0) : NMETA + 32 * qs + c;
;     const int trb = (4 * h + ((lane & 15) >> 2)) * PB + 16 * ((lane >> 4) & 1) + 4 * (lane & 3);
;     const int qrow0 = metaq ? SEQ : 32 * qs;
;     LAS bf16x8* qs_lds = (LAS bf16x8*)(vs + 32 * PB) + lane;
;     { const bf16_t* qp = z + zrowU(qrow0, 32) + zlaneRC(c, hh * 128 + 8 * h);
;       bf16x8 qf[8];
; #pragma unroll
;       for (int s = 0; s < 8; ++s) qf[s] = *(const bf16x8*)(qp + (((s >> 1) << 9) | ((s & 1) << 8)));
;       asm volatile("s_waitcnt lgkmcnt(0)" ::: "memory");
; #pragma unroll
;       for (int s = 0; s < 8; ++s) qs_lds[64 * s] = qf[s]; }
;     f32x16 acc[4];
; #pragma unroll
;     for (int dt = 0; dt < 4; ++dt)
; #pragma unroll
;         for (int i = 0; i < 16; ++i) acc[dt][i] = 0.f;
;     float later = 0.f;
;     int t = metaq ? -1 : qs;
;     const int tfirst = t;
;     const bf16_t* kbase = z + zlaneRC(c, 2048 + hh * 128 + 8 * h);
;     const bf16_t* vbase = z + zlaneRC(lane & 15, 4096 + hh * 128 + 8 * (lane >> 4));
;     bf16x8 kf[8]; u32x4 vv[8];
;     { const size_t ro = zrowU(t < 0 ? SEQ : 32 * t, 32);
; #pragma unroll
;       for (int s = 0; s < 8; ++s) kf[s] = *(const bf16x8*)(kbase + ro + (((s >> 1) << 9) | ((s & 1) << 8)));
; #pragma unroll
;       for (int i = 0; i < 8; ++i) vv[i] = *(const u32x4*)(vbase + ro + (((i >> 2) << 13) | ((i & 3) << 9))); }
.Lpq_skipQ_B:
	v_ashrrev_i32_e32 v41, 1, v2
	s_max_i32 s28, s6, -1
	v_bfe_u32 v0, v2, 2, 2
	v_lshlrev_b32_e32 v183, 2, v180
	v_and_b32_e32 v42, -8, v41
	s_add_i32 s4, s27, 0x1000
	s_lshl_b32 s6, s28, 5
	v_or_b32_e32 v44, v183, v0
	v_add_u32_e32 v0, s4, v42
	s_and_b64 s[4:5], exec, s[0:1]
	s_cselect_b32 s4, s6, 0x4000
	s_lshl_b32 s6, s4, 8
	s_lshl_b32 s7, s4, 9
	s_ashr_i32 s5, s4, 3
	s_lshl_b32 s8, s4, 5
	s_and_b32 s6, s6, 0x8000
	s_and_b32 s7, s7, 0x4000
	v_and_b32_e32 v38, 15, v2
	v_lshlrev_b32_e32 v45, 8, v0
	v_lshlrev_b32_e32 v0, 5, v0
	v_or_b32_e32 v3, v3, v36
	s_and_b32 s4, s5, 0xffffffe0
	s_and_b32 s8, s8, 0x800
	s_or_b32 s6, s6, s7
	v_lshlrev_b32_e32 v41, 4, v41
	v_lshlrev_b32_e32 v43, 3, v38
	v_and_b32_e32 v36, 0x1000, v0
	v_or3_b32 v0, v3, v37, v181
	s_ashr_i32 s5, s4, 31
	s_or_b32 s6, s6, s8
	v_and_b32_e32 v41, 0x780, v41
	v_and_or_b32 v43, v45, s12, v43
	v_add_u32_e32 v0, 0x80000, v0
	s_lshl_b64 s[4:5], s[4:5], 17
	s_lshl_b32 s6, s6, 1
	v_lshl_add_u64 v[158:159], v[0:1], 1, s[82:83]
	v_or3_b32 v0, v43, v36, v41
	s_or_b32 s4, s4, s6
	v_lshl_add_u32 v182, v2, 4, s25
	s_waitcnt lgkmcnt(0)
	v_lshl_add_u64 v[36:37], v[158:159], 0, s[4:5]
	v_lshl_add_u64 v[160:161], v[0:1], 1, s[82:83]
	s_bitcmp1_b32 s101, 31
	s_cbranch_scc1 .Lpq_skipK_B
	global_load_dwordx4 v[114:117], v[36:37], off
	global_load_dwordx4 v[118:121], v[36:37], off offset:512
	global_load_dwordx4 v[122:125], v[36:37], off offset:1024
	global_load_dwordx4 v[126:129], v[36:37], off offset:1536
.Lpq_skipK_B:
	v_and_b32_e32 v40, 16, v2
	v_lshlrev_b32_e32 v3, 3, v2
	v_lshlrev_b32_e32 v0, 1, v40
	v_and_b32_e32 v3, 24, v3
	v_lshlrev_b32_e32 v39, 2, v2
	v_add3_u32 v3, s25, v0, v3
	v_cmp_gt_u32_e64 s[36:37], 32, v2
	v_mov_b32_e32 v189, 0
	v_xor_b32_e32 v184, 0x80, v39
	v_or_b32_e32 v185, 1, v183
	v_or_b32_e32 v186, 2, v183
	v_or_b32_e32 v187, 3, v183
	v_add_u32_e32 v163, 10, v183
	v_add_u32_e32 v0, 8, v183
	v_add_u32_e32 v165, 11, v183
	v_add_u32_e32 v162, 9, v183
	v_add_u32_e32 v167, 18, v183
	v_add_u32_e32 v164, 16, v183
	v_add_u32_e32 v169, 19, v183
	v_add_u32_e32 v166, 17, v183
	v_add_u32_e32 v171, 26, v183
	s_bitcmp1_b32 s101, 31
	s_cbranch_scc1 .Lpq_skipL_B
	s_waitcnt vmcnt(11)
	ds_write_b128 v182, v[4:7] offset:10240
	s_waitcnt vmcnt(10)
	ds_write_b128 v182, v[8:11] offset:11264
	s_waitcnt vmcnt(9)
	ds_write_b128 v182, v[12:15] offset:12288
	s_waitcnt vmcnt(8)
	ds_write_b128 v182, v[16:19] offset:13312
	s_waitcnt vmcnt(7)
	ds_write_b128 v182, v[20:23] offset:14336
	s_waitcnt vmcnt(6)
	ds_write_b128 v182, v[24:27] offset:15360
	s_waitcnt vmcnt(5)
	ds_write_b128 v182, v[28:31] offset:16384
	s_waitcnt vmcnt(4)
	ds_write_b128 v182, v[32:35] offset:17408
	v_lshl_add_u64 v[4:5], v[160:161], 0, s[4:5]
	global_load_dwordx4 v[130:133], v[36:37], off offset:2048
	global_load_dwordx4 v[134:137], v[36:37], off offset:2560
	global_load_dwordx4 v[138:141], v[36:37], off offset:3072
	global_load_dwordx4 v[142:145], v[36:37], off offset:3584
	global_load_dwordx4 v[82:85], v[4:5], off
	global_load_dwordx4 v[86:89], v[4:5], off offset:1024
	global_load_dwordx4 v[90:93], v[4:5], off offset:2048
	global_load_dwordx4 v[94:97], v[4:5], off offset:3072
	v_add_co_u32_e32 v4, vcc, s3, v4
	s_movk_i32 s4, 0x140
	s_nop 0
	v_addc_co_u32_e32 v5, vcc, 0, v5, vcc
	global_load_dwordx4 v[98:101], v[4:5], off
	global_load_dwordx4 v[102:105], v[4:5], off offset:1024
	global_load_dwordx4 v[106:109], v[4:5], off offset:2048
	global_load_dwordx4 v[110:113], v[4:5], off offset:3072
.Lpq_skipL_B:
	s_movk_i32 s4, 0x140
	s_mov_b32 s101, 0
	v_mul_lo_u32 v2, v44, s4
	v_mul_u32_u24_e32 v4, 0x140, v38
	v_lshlrev_b32_e32 v5, 1, v42
	v_add_u32_e32 v168, 24, v183
	v_add_u32_e32 v173, 27, v183
	v_add_u32_e32 v170, 25, v183
	v_add3_u32 v188, s25, v4, v5
	v_add_u32_e32 v190, v3, v2
	s_mov_b32 s30, s28
	v_mov_b32_e32 v50, 0
	v_mov_b32_e32 v51, v189
	v_mov_b32_e32 v52, v189
	v_mov_b32_e32 v53, v189
	v_mov_b32_e32 v54, v189
	v_mov_b32_e32 v55, v189
	v_mov_b32_e32 v56, v189
	v_mov_b32_e32 v57, v189
	v_mov_b32_e32 v58, v189
	v_mov_b32_e32 v59, v189
	v_mov_b32_e32 v60, v189
	v_mov_b32_e32 v61, v189
	v_mov_b32_e32 v62, v189
	v_mov_b32_e32 v63, v189
	v_mov_b32_e32 v64, v189
	v_mov_b32_e32 v65, v189
	v_mov_b32_e32 v34, 0
	v_mov_b32_e32 v35, v189
	v_mov_b32_e32 v36, v189
	v_mov_b32_e32 v37, v189
	v_mov_b32_e32 v38, v189
	v_mov_b32_e32 v39, v189
	v_mov_b32_e32 v40, v189
	v_mov_b32_e32 v41, v189
	v_mov_b32_e32 v42, v189
	v_mov_b32_e32 v43, v189
	v_mov_b32_e32 v44, v189
	v_mov_b32_e32 v45, v189
	v_mov_b32_e32 v46, v189
	v_mov_b32_e32 v47, v189
	v_mov_b32_e32 v48, v189
	v_mov_b32_e32 v49, v189
	v_mov_b32_e32 v18, 0
	v_mov_b32_e32 v19, v189
	v_mov_b32_e32 v20, v189
	v_mov_b32_e32 v21, v189
	v_mov_b32_e32 v22, v189
	v_mov_b32_e32 v23, v189
	v_mov_b32_e32 v24, v189
	v_mov_b32_e32 v25, v189
	v_mov_b32_e32 v26, v189
	v_mov_b32_e32 v27, v189
	v_mov_b32_e32 v28, v189
	v_mov_b32_e32 v29, v189
	v_mov_b32_e32 v30, v189
	v_mov_b32_e32 v31, v189
	v_mov_b32_e32 v32, v189
	v_mov_b32_e32 v33, v189
	v_mov_b32_e32 v2, 0
	v_mov_b32_e32 v3, v189
	v_mov_b32_e32 v4, v189
	v_mov_b32_e32 v5, v189
	v_mov_b32_e32 v6, v189
	v_mov_b32_e32 v7, v189
	v_mov_b32_e32 v8, v189
	v_mov_b32_e32 v9, v189
	v_mov_b32_e32 v10, v189
	v_mov_b32_e32 v11, v189
	v_mov_b32_e32 v12, v189
	v_mov_b32_e32 v13, v189
	v_mov_b32_e32 v14, v189
	v_mov_b32_e32 v15, v189
	v_mov_b32_e32 v16, v189
	v_mov_b32_e32 v17, v189
	s_branch .LBB0_151

; DI size_t zrowU(int row0, int NT) { return ((size_t)((row0 >> 8) * NT) << 16) + (size_t)((((row0 >> 7) & 1) << 15) | (((row0 >> 5) & 1) << 14) | (((row0 >> 6) & 1) << 11)); }
; DI unsigned zlaneRC(int r5, int col) { return (unsigned)(((col >> 8) << 16) | ((r5 >> 4) << 13) | (((col >> 7) & 1) << 12) | (((col >> 5) & 3) << 9) | (((col >> 3) & 3) << 7) | ((r5 & 15) << 3) | (col & 7)); }
; DI void attnB_item(bf16_t* z, int hh, int qs, LAS bf16_t* vs, int lane) {
;     ...
;     if (!metaq || c < NMETA) {
;         bf16_t* orow = z + zrowU(qrow0, 32) + zlaneRC(c, hh * 128 + 4 * h);
;         const bf16_t* grow = z + zrowU(qrow0, 32) + zlaneRC(c, 6144 + hh * 128 + 4 * h);
; #pragma unroll
;         for (int dt = 0; dt < 4; ++dt)
; #pragma unroll
;             for (int g = 0; g < 4; ++g) {
;                 const int d0 = (dt << 9) | (g << 7);
;                 const u32x2 gv = *(const u32x2*)(grow + d0);
; DI bool attn_next(AttnQueue& q, int lane0, int& qs, int& hd) {
;     for (;;) {
;         if (q.cur >= 8) return false;
;         const int xq = (q.x + q.cur) & 7;
;         const int nqs = NQS / 8 + (xq == 7 ? 1 : 0);
;         unsigned n = 0;
;         if (lane0) n = __hip_atomic_fetch_add(q.heads + 64 * xq, 1u, __ATOMIC_RELAXED, __HIP_MEMORY_SCOPE_AGENT);
;         n = (unsigned)__builtin_amdgcn_readfirstlane((int)n);
;         if (n < (unsigned)(nqs * 16)) { qs = (NQS / 8) * xq + (int)(n >> 4); hd = (int)(n & 15u); return true; }
.LBB0_157:
	v_cmp_gt_u32_e32 vcc, 16, v178
	s_or_b64 s[0:1], s[0:1], vcc
	s_and_saveexec_b64 s[4:5], s[0:1]
	s_xor_b64 s[0:1], exec, s[4:5]
	s_cbranch_execz .LBB0_130
	s_mov_b64 vcc, exec
	s_mov_b64 exec, -1
	v_add_u32_e32 v0, s27, v183
	v_lshlrev_b32_e32 v66, 8, v0
	v_lshlrev_b32_e32 v0, 5, v0
	v_lshlrev_b32_e32 v67, 6, v180
	v_and_b32_e32 v0, 0x1000, v0
	v_and_b32_e32 v68, 0x780, v67
	v_and_b32_e32 v69, 4, v183
	v_or_b32_e32 v67, v68, v69
	v_and_or_b32 v70, v66, s12, v0
	v_or3_b32 v0, v67, v181, v70
	v_lshl_add_u64 v[146:147], v[0:1], 1, s[46:47]
	v_or3_b32 v0, v70, v69, v68
	s_mov_b32 s4, 0x180000
	v_add3_u32 v0, v0, v181, s4
	v_lshl_add_u64 v[148:149], v[0:1], 1, s[46:47]
	s_add_i32 s5, s26, s33
	s_and_b32 s5, s5, 7
	s_lshl_b32 s6, s5, 8
	s_mov_b64 exec, 1
	v_mov_b32_e32 v66, s6
	v_mov_b32_e32 v67, 1
	global_atomic_add v240, v66, v67, s[34:35] sc0
	s_mov_b64 exec, vcc
	global_load_dwordx2 v[192:193], v[148:149], off
	global_load_dwordx2 v[194:195], v[148:149], off offset:256
	global_load_dwordx2 v[196:197], v[148:149], off offset:512
	global_load_dwordx2 v[198:199], v[148:149], off offset:768
	global_load_dwordx2 v[200:201], v[148:149], off offset:1024
	global_load_dwordx2 v[202:203], v[148:149], off offset:1280
	global_load_dwordx2 v[204:205], v[148:149], off offset:1536
	global_load_dwordx2 v[206:207], v[148:149], off offset:1792
	global_load_dwordx2 v[208:209], v[148:149], off offset:2048
	global_load_dwordx2 v[210:211], v[148:149], off offset:2304
	global_load_dwordx2 v[212:213], v[148:149], off offset:2560
	global_load_dwordx2 v[214:215], v[148:149], off offset:2816
	global_load_dwordx2 v[216:217], v[148:149], off offset:3072
	global_load_dwordx2 v[218:219], v[148:149], off offset:3328
	global_load_dwordx2 v[220:221], v[148:149], off offset:3584
	global_load_dwordx2 v[222:223], v[148:149], off offset:3840
	s_waitcnt vmcnt(16)
	s_mov_b64 exec, -1
	v_readfirstlane_b32 s6, v240
	v_mov_b64_e32 v[150:151], v[148:149]
	v_mov_b64_e32 v[74:75], v[148:149]
	v_mov_b64_e32 v[76:77], v[148:149]
	v_mov_b64_e32 v[78:79], v[148:149]
	s_cmp_eq_u32 s5, 7
	s_cselect_b32 s7, s14, 0x400
	s_mov_b32 s101, 0
	s_cmp_lt_u32 s6, s7
	s_cbranch_scc0 .Lpq_dma_B
	s_lshr_b32 s8, s6, 4
	s_sub_i32 s9, 63, s8
	s_cmp_lt_u32 s8, 64
	s_cselect_b32 s8, s9, s8
	s_lshl_b32 s9, s5, 6
	s_add_i32 s8, s8, s9
	s_and_b32 s9, s6, 15
	s_lshl_b32 s10, s9, 12
	s_or_b32 s101, s8, s10
	s_bitset1_b32 s101, 31
	s_lshl_b32 s10, s8, 5
	s_cmp_lt_u32 s8, 0x200
	s_cselect_b32 s10, s10, 0x4000
	s_lshr_b32 s11, s10, 3
	s_and_b32 s78, s11, 0x1fffffe0
	s_lshl_b32 s11, s10, 8
	s_and_b32 s11, s11, 0x8000
	s_lshl_b32 s7, s10, 9
	s_and_b32 s7, s7, 0x4000
	s_or_b32 s11, s11, s7
	s_lshl_b32 s7, s10, 5
	s_and_b32 s7, s7, 0x800
	s_or_b32 s11, s11, s7
	s_lshl_b32 s10, s78, 17
	s_lshl_b32 s11, s11, 1
	s_or_b32 s10, s10, s11
	s_mov_b32 s11, 0
	s_add_u32 s6, s82, s10
	s_addc_u32 s7, s83, 0
	s_lshr_b32 s4, s27, 7
	s_lshr_b32 s5, s4, 1
	s_lshl_b32 s5, s5, 17
	s_and_b32 s4, s4, 1
	s_lshl_b32 s4, s4, 13
	s_or_b32 s4, s4, s5
	s_lshr_b32 s5, s9, 1
	s_lshl_b32 s5, s5, 17
	s_and_b32 s78, s9, 1
	s_lshl_b32 s78, s78, 13
	s_or_b32 s5, s5, s78
	s_sub_i32 s4, s5, s4
	s_ashr_i32 s5, s4, 31
	v_lshl_add_u64 v[158:159], v[158:159], 0, s[4:5]
	v_lshl_add_u64 v[160:161], v[160:161], 0, s[4:5]
	v_lshl_add_u64 v[74:75], v[158:159], 0, s[10:11]
	v_lshl_add_u64 v[76:77], v[160:161], 0, s[10:11]
	s_movk_i32 s4, 0x4000
	s_mov_b32 s5, 0
	v_lshl_add_u64 v[78:79], v[76:77], 0, s[4:5]
	s_lshl_b32 s9, s9, 7
	v_lshl_add_u32 v150, v180, 3, s9
	v_lshlrev_b32_e32 v151, 8, v150
	v_lshlrev_b32_e32 v150, 5, v150
	v_and_b32_e32 v150, 0x1000, v150
	v_and_b32_e32 v151, 0xffff0000, v151
	v_lshlrev_b32_e32 v152, 7, v180
	v_and_b32_e32 v152, 0x780, v152
	v_or3_b32 v150, v150, v151, v152
	v_or_b32_e32 v150, v150, v181
	v_mov_b32_e32 v151, 0
	v_lshl_add_u64 v[150:151], v[150:151], 1, s[6:7]
.Lpq_dma_B:
	s_add_i32 s8, s25, 0x2800
	s_mov_b32 m0, s8
	s_nop 0
	global_load_lds_dwordx4 v[150:151], off
	s_add_i32 m0, s8, 0x200
	s_nop 0
	global_load_lds_dwordx4 v[150:151], off offset:512
	s_add_i32 m0, s8, 0x400
	s_nop 0
	global_load_lds_dwordx4 v[150:151], off offset:1024
	s_add_i32 m0, s8, 0x600
	s_nop 0
	global_load_lds_dwordx4 v[150:151], off offset:1536
	s_add_i32 m0, s8, 0x800
	s_nop 0
	global_load_lds_dwordx4 v[150:151], off offset:2048
	s_add_i32 m0, s8, 0xa00
	s_nop 0
	global_load_lds_dwordx4 v[150:151], off offset:2560
	s_add_i32 m0, s8, 0xc00
	s_nop 0
	global_load_lds_dwordx4 v[150:151], off offset:3072
	s_add_i32 m0, s8, 0xe00
	s_nop 0
	global_load_lds_dwordx4 v[150:151], off offset:3584
	global_load_dwordx4 v[114:117], v[74:75], off
	global_load_dwordx4 v[118:121], v[74:75], off offset:512
	global_load_dwordx4 v[122:125], v[74:75], off offset:1024
	global_load_dwordx4 v[126:129], v[74:75], off offset:1536
	global_load_dwordx4 v[130:133], v[74:75], off offset:2048
	global_load_dwordx4 v[134:137], v[74:75], off offset:2560
	global_load_dwordx4 v[138:141], v[74:75], off offset:3072
	global_load_dwordx4 v[142:145], v[74:75], off offset:3584
	global_load_dwordx4 v[82:85], v[76:77], off
	global_load_dwordx4 v[86:89], v[76:77], off offset:1024
	global_load_dwordx4 v[90:93], v[76:77], off offset:2048
	global_load_dwordx4 v[94:97], v[76:77], off offset:3072
	global_load_dwordx4 v[98:101], v[78:79], off
	global_load_dwordx4 v[102:105], v[78:79], off offset:1024
	global_load_dwordx4 v[106:109], v[78:79], off offset:2048
	global_load_dwordx4 v[110:113], v[78:79], off offset:3072
	s_mov_b64 exec, vcc
	s_waitcnt vmcnt(39)
; DI unsigned pk2(float a, float b) { f32x2 v = {a, b}; bf16v2 r = __builtin_convertvector(v, bf16v2); return __builtin_bit_cast(unsigned, r); }
; DI float bf_lo(unsigned u) { return __uint_as_float(u << 16); }
; DI float bf_hi(unsigned u) { return __uint_as_float(u & 0xffff0000u); }
; DI float silu_mul(float o, float g) { return o * g * __builtin_amdgcn_rcpf(1.0f + __builtin_amdgcn_exp2f(g * -1.4426950408889634f)); }
; DI void attnB_item(bf16_t* z, int hh, int qs, LAS bf16_t* vs, int lane) {
;     ...
;         for (int dt = 0; dt < 4; ++dt)
; #pragma unroll
;             for (int g = 0; g < 4; ++g) {
;                 const int d0 = (dt << 9) | (g << 7);
;                 const u32x2 gv = *(const u32x2*)(grow + d0);
;                 u32x2 o; o.x = pk2(silu_mul(acc[dt][4 * g], bf_lo(gv.x)), silu_mul(acc[dt][4 * g + 1], bf_hi(gv.x)));
;                 o.y = pk2(silu_mul(acc[dt][4 * g + 2], bf_lo(gv.y)), silu_mul(acc[dt][4 * g + 3], bf_hi(gv.y)));
;                 *(u32x2*)(orow + d0) = o;
;             }
	v_lshlrev_b32_e32 v66, 16, v192
	v_and_b32_e32 v67, 0xffff0000, v192
	v_lshlrev_b32_e32 v68, 16, v193
	v_and_b32_e32 v69, 0xffff0000, v193
	v_mul_f32_e32 v70, 0xbfb8aa3b, v66
	v_mul_f32_e32 v71, 0xbfb8aa3b, v67
	v_mul_f32_e32 v72, 0xbfb8aa3b, v68
	v_mul_f32_e32 v73, 0xbfb8aa3b, v69
	v_exp_f32_e32 v70, v70
	v_exp_f32_e32 v71, v71
	v_exp_f32_e32 v72, v72
	v_exp_f32_e32 v73, v73
	v_pk_mul_f32 v[50:51], v[50:51], v[66:67]
	v_pk_mul_f32 v[52:53], v[52:53], v[68:69]
	v_add_f32_e32 v70, 1.0, v70
	v_add_f32_e32 v71, 1.0, v71
	v_add_f32_e32 v72, 1.0, v72
	v_add_f32_e32 v73, 1.0, v73
	v_rcp_f32_e32 v70, v70
	v_rcp_f32_e32 v71, v71
	v_rcp_f32_e32 v72, v72
	v_rcp_f32_e32 v73, v73
	v_pk_mul_f32 v[50:51], v[50:51], v[70:71]
	v_pk_mul_f32 v[52:53], v[52:53], v[72:73]
	v_cvt_pk_bf16_f32 v50, v50, v51
	v_cvt_pk_bf16_f32 v51, v52, v53
	s_waitcnt vmcnt(38)
	v_lshlrev_b32_e32 v74, 16, v194
	v_and_b32_e32 v75, 0xffff0000, v194
	v_lshlrev_b32_e32 v76, 16, v195
	v_and_b32_e32 v77, 0xffff0000, v195
	v_mul_f32_e32 v78, 0xbfb8aa3b, v74
	v_mul_f32_e32 v79, 0xbfb8aa3b, v75
	v_mul_f32_e32 v80, 0xbfb8aa3b, v76
	v_mul_f32_e32 v81, 0xbfb8aa3b, v77
	v_exp_f32_e32 v78, v78
	v_exp_f32_e32 v79, v79
	v_exp_f32_e32 v80, v80
	v_exp_f32_e32 v81, v81
	v_pk_mul_f32 v[54:55], v[54:55], v[74:75]
	v_pk_mul_f32 v[56:57], v[56:57], v[76:77]
	v_add_f32_e32 v78, 1.0, v78
	v_add_f32_e32 v79, 1.0, v79
	v_add_f32_e32 v80, 1.0, v80
	v_add_f32_e32 v81, 1.0, v81
	v_rcp_f32_e32 v78, v78
	v_rcp_f32_e32 v79, v79
	v_rcp_f32_e32 v80, v80
	v_rcp_f32_e32 v81, v81
	v_pk_mul_f32 v[54:55], v[54:55], v[78:79]
	v_pk_mul_f32 v[56:57], v[56:57], v[80:81]
	v_cvt_pk_bf16_f32 v54, v54, v55
	v_cvt_pk_bf16_f32 v55, v56, v57
	s_waitcnt vmcnt(37)
	v_lshlrev_b32_e32 v66, 16, v196
	v_and_b32_e32 v67, 0xffff0000, v196
	v_lshlrev_b32_e32 v68, 16, v197
	v_and_b32_e32 v69, 0xffff0000, v197
	v_mul_f32_e32 v70, 0xbfb8aa3b, v66
	v_mul_f32_e32 v71, 0xbfb8aa3b, v67
	v_mul_f32_e32 v72, 0xbfb8aa3b, v68
	v_mul_f32_e32 v73, 0xbfb8aa3b, v69
	v_exp_f32_e32 v70, v70
	v_exp_f32_e32 v71, v71
	v_exp_f32_e32 v72, v72
	v_exp_f32_e32 v73, v73
	v_pk_mul_f32 v[58:59], v[58:59], v[66:67]
	v_pk_mul_f32 v[60:61], v[60:61], v[68:69]
	v_add_f32_e32 v70, 1.0, v70
	v_add_f32_e32 v71, 1.0, v71
	v_add_f32_e32 v72, 1.0, v72
	v_add_f32_e32 v73, 1.0, v73
	v_rcp_f32_e32 v70, v70
	v_rcp_f32_e32 v71, v71
	v_rcp_f32_e32 v72, v72
	v_rcp_f32_e32 v73, v73
	v_pk_mul_f32 v[58:59], v[58:59], v[70:71]
	v_pk_mul_f32 v[60:61], v[60:61], v[72:73]
	v_cvt_pk_bf16_f32 v58, v58, v59
	v_cvt_pk_bf16_f32 v59, v60, v61
	s_waitcnt vmcnt(36)
	v_lshlrev_b32_e32 v74, 16, v198
	v_and_b32_e32 v75, 0xffff0000, v198
	v_lshlrev_b32_e32 v76, 16, v199
	v_and_b32_e32 v77, 0xffff0000, v199
	v_mul_f32_e32 v78, 0xbfb8aa3b, v74
	v_mul_f32_e32 v79, 0xbfb8aa3b, v75
	v_mul_f32_e32 v80, 0xbfb8aa3b, v76
	v_mul_f32_e32 v81, 0xbfb8aa3b, v77
	v_exp_f32_e32 v78, v78
	v_exp_f32_e32 v79, v79
	v_exp_f32_e32 v80, v80
	v_exp_f32_e32 v81, v81
	v_pk_mul_f32 v[62:63], v[62:63], v[74:75]
	v_pk_mul_f32 v[64:65], v[64:65], v[76:77]
	v_add_f32_e32 v78, 1.0, v78
	v_add_f32_e32 v79, 1.0, v79
	v_add_f32_e32 v80, 1.0, v80
	v_add_f32_e32 v81, 1.0, v81
	v_rcp_f32_e32 v78, v78
	v_rcp_f32_e32 v79, v79
	v_rcp_f32_e32 v80, v80
	v_rcp_f32_e32 v81, v81
	v_pk_mul_f32 v[62:63], v[62:63], v[78:79]
	v_pk_mul_f32 v[64:65], v[64:65], v[80:81]
	v_cvt_pk_bf16_f32 v62, v62, v63
	v_cvt_pk_bf16_f32 v63, v64, v65
	s_waitcnt vmcnt(35)
	v_lshlrev_b32_e32 v66, 16, v200
	v_and_b32_e32 v67, 0xffff0000, v200
	v_lshlrev_b32_e32 v68, 16, v201
	v_and_b32_e32 v69, 0xffff0000, v201
	v_mul_f32_e32 v70, 0xbfb8aa3b, v66
	v_mul_f32_e32 v71, 0xbfb8aa3b, v67
	v_mul_f32_e32 v72, 0xbfb8aa3b, v68
	v_mul_f32_e32 v73, 0xbfb8aa3b, v69
	v_exp_f32_e32 v70, v70
	v_exp_f32_e32 v71, v71
	v_exp_f32_e32 v72, v72
	v_exp_f32_e32 v73, v73
	v_pk_mul_f32 v[34:35], v[34:35], v[66:67]
	v_pk_mul_f32 v[36:37], v[36:37], v[68:69]
	v_add_f32_e32 v70, 1.0, v70
	v_add_f32_e32 v71, 1.0, v71
	v_add_f32_e32 v72, 1.0, v72
	v_add_f32_e32 v73, 1.0, v73
	v_rcp_f32_e32 v70, v70
	v_rcp_f32_e32 v71, v71
	v_rcp_f32_e32 v72, v72
	v_rcp_f32_e32 v73, v73
	v_pk_mul_f32 v[34:35], v[34:35], v[70:71]
	v_pk_mul_f32 v[36:37], v[36:37], v[72:73]
	v_cvt_pk_bf16_f32 v34, v34, v35
	v_cvt_pk_bf16_f32 v35, v36, v37
	s_waitcnt vmcnt(34)
	v_lshlrev_b32_e32 v74, 16, v202
	v_and_b32_e32 v75, 0xffff0000, v202
	v_lshlrev_b32_e32 v76, 16, v203
	v_and_b32_e32 v77, 0xffff0000, v203
	v_mul_f32_e32 v78, 0xbfb8aa3b, v74
	v_mul_f32_e32 v79, 0xbfb8aa3b, v75
	v_mul_f32_e32 v80, 0xbfb8aa3b, v76
	v_mul_f32_e32 v81, 0xbfb8aa3b, v77
	v_exp_f32_e32 v78, v78
	v_exp_f32_e32 v79, v79
	v_exp_f32_e32 v80, v80
	v_exp_f32_e32 v81, v81
	v_pk_mul_f32 v[38:39], v[38:39], v[74:75]
	v_pk_mul_f32 v[40:41], v[40:41], v[76:77]
	v_add_f32_e32 v78, 1.0, v78
	v_add_f32_e32 v79, 1.0, v79
	v_add_f32_e32 v80, 1.0, v80
	v_add_f32_e32 v81, 1.0, v81
	v_rcp_f32_e32 v78, v78
	v_rcp_f32_e32 v79, v79
	v_rcp_f32_e32 v80, v80
	v_rcp_f32_e32 v81, v81
	v_pk_mul_f32 v[38:39], v[38:39], v[78:79]
	v_pk_mul_f32 v[40:41], v[40:41], v[80:81]
	v_cvt_pk_bf16_f32 v38, v38, v39
	v_cvt_pk_bf16_f32 v39, v40, v41
	s_waitcnt vmcnt(33)
	v_lshlrev_b32_e32 v66, 16, v204
	v_and_b32_e32 v67, 0xffff0000, v204
	v_lshlrev_b32_e32 v68, 16, v205
	v_and_b32_e32 v69, 0xffff0000, v205
	v_mul_f32_e32 v70, 0xbfb8aa3b, v66
	v_mul_f32_e32 v71, 0xbfb8aa3b, v67
	v_mul_f32_e32 v72, 0xbfb8aa3b, v68
	v_mul_f32_e32 v73, 0xbfb8aa3b, v69
	v_exp_f32_e32 v70, v70
	v_exp_f32_e32 v71, v71
	v_exp_f32_e32 v72, v72
	v_exp_f32_e32 v73, v73
	v_pk_mul_f32 v[42:43], v[42:43], v[66:67]
	v_pk_mul_f32 v[44:45], v[44:45], v[68:69]
	v_add_f32_e32 v70, 1.0, v70
	v_add_f32_e32 v71, 1.0, v71
	v_add_f32_e32 v72, 1.0, v72
	v_add_f32_e32 v73, 1.0, v73
	v_rcp_f32_e32 v70, v70
	v_rcp_f32_e32 v71, v71
	v_rcp_f32_e32 v72, v72
	v_rcp_f32_e32 v73, v73
	v_pk_mul_f32 v[42:43], v[42:43], v[70:71]
	v_pk_mul_f32 v[44:45], v[44:45], v[72:73]
	v_cvt_pk_bf16_f32 v42, v42, v43
	v_cvt_pk_bf16_f32 v43, v44, v45
	s_waitcnt vmcnt(32)
; DI unsigned pk2(float a, float b) { f32x2 v = {a, b}; bf16v2 r = __builtin_convertvector(v, bf16v2); return __builtin_bit_cast(unsigned, r); }
; DI float bf_lo(unsigned u) { return __uint_as_float(u << 16); }
; DI float bf_hi(unsigned u) { return __uint_as_float(u & 0xffff0000u); }
; DI float silu_mul(float o, float g) { return o * g * __builtin_amdgcn_rcpf(1.0f + __builtin_amdgcn_exp2f(g * -1.4426950408889634f)); }
; DI void attnB_item(bf16_t* z, int hh, int qs, LAS bf16_t* vs, int lane) {
;     ...
;         for (int dt = 0; dt < 4; ++dt)
; #pragma unroll
;             for (int g = 0; g < 4; ++g) {
;                 const int d0 = (dt << 9) | (g << 7);
;                 const u32x2 gv = *(const u32x2*)(grow + d0);
;                 u32x2 o; o.x = pk2(silu_mul(acc[dt][4 * g], bf_lo(gv.x)), silu_mul(acc[dt][4 * g + 1], bf_hi(gv.x)));
;                 o.y = pk2(silu_mul(acc[dt][4 * g + 2], bf_lo(gv.y)), silu_mul(acc[dt][4 * g + 3], bf_hi(gv.y)));
;                 *(u32x2*)(orow + d0) = o;
;             }
	v_lshlrev_b32_e32 v74, 16, v206
	v_and_b32_e32 v75, 0xffff0000, v206
	v_lshlrev_b32_e32 v76, 16, v207
	v_and_b32_e32 v77, 0xffff0000, v207
	v_mul_f32_e32 v78, 0xbfb8aa3b, v74
	v_mul_f32_e32 v79, 0xbfb8aa3b, v75
	v_mul_f32_e32 v80, 0xbfb8aa3b, v76
	v_mul_f32_e32 v81, 0xbfb8aa3b, v77
	v_exp_f32_e32 v78, v78
	v_exp_f32_e32 v79, v79
	v_exp_f32_e32 v80, v80
	v_exp_f32_e32 v81, v81
	v_pk_mul_f32 v[46:47], v[46:47], v[74:75]
	v_pk_mul_f32 v[48:49], v[48:49], v[76:77]
	v_add_f32_e32 v78, 1.0, v78
	v_add_f32_e32 v79, 1.0, v79
	v_add_f32_e32 v80, 1.0, v80
	v_add_f32_e32 v81, 1.0, v81
	v_rcp_f32_e32 v78, v78
	v_rcp_f32_e32 v79, v79
	v_rcp_f32_e32 v80, v80
	v_rcp_f32_e32 v81, v81
	v_pk_mul_f32 v[46:47], v[46:47], v[78:79]
	v_pk_mul_f32 v[48:49], v[48:49], v[80:81]
	v_cvt_pk_bf16_f32 v46, v46, v47
	v_cvt_pk_bf16_f32 v47, v48, v49
	s_waitcnt vmcnt(31)
	v_lshlrev_b32_e32 v66, 16, v208
	v_and_b32_e32 v67, 0xffff0000, v208
	v_lshlrev_b32_e32 v68, 16, v209
	v_and_b32_e32 v69, 0xffff0000, v209
	v_mul_f32_e32 v70, 0xbfb8aa3b, v66
	v_mul_f32_e32 v71, 0xbfb8aa3b, v67
	v_mul_f32_e32 v72, 0xbfb8aa3b, v68
	v_mul_f32_e32 v73, 0xbfb8aa3b, v69
	v_exp_f32_e32 v70, v70
	v_exp_f32_e32 v71, v71
	v_exp_f32_e32 v72, v72
	v_exp_f32_e32 v73, v73
	v_pk_mul_f32 v[18:19], v[18:19], v[66:67]
	v_pk_mul_f32 v[20:21], v[20:21], v[68:69]
	v_add_f32_e32 v70, 1.0, v70
	v_add_f32_e32 v71, 1.0, v71
	v_add_f32_e32 v72, 1.0, v72
	v_add_f32_e32 v73, 1.0, v73
	v_rcp_f32_e32 v70, v70
	v_rcp_f32_e32 v71, v71
	v_rcp_f32_e32 v72, v72
	v_rcp_f32_e32 v73, v73
	v_pk_mul_f32 v[18:19], v[18:19], v[70:71]
	v_pk_mul_f32 v[20:21], v[20:21], v[72:73]
	v_cvt_pk_bf16_f32 v18, v18, v19
	v_cvt_pk_bf16_f32 v19, v20, v21
	s_waitcnt vmcnt(30)
	v_lshlrev_b32_e32 v74, 16, v210
	v_and_b32_e32 v75, 0xffff0000, v210
	v_lshlrev_b32_e32 v76, 16, v211
	v_and_b32_e32 v77, 0xffff0000, v211
	v_mul_f32_e32 v78, 0xbfb8aa3b, v74
	v_mul_f32_e32 v79, 0xbfb8aa3b, v75
	v_mul_f32_e32 v80, 0xbfb8aa3b, v76
	v_mul_f32_e32 v81, 0xbfb8aa3b, v77
	v_exp_f32_e32 v78, v78
	v_exp_f32_e32 v79, v79
	v_exp_f32_e32 v80, v80
	v_exp_f32_e32 v81, v81
	v_pk_mul_f32 v[22:23], v[22:23], v[74:75]
	v_pk_mul_f32 v[24:25], v[24:25], v[76:77]
	v_add_f32_e32 v78, 1.0, v78
	v_add_f32_e32 v79, 1.0, v79
	v_add_f32_e32 v80, 1.0, v80
	v_add_f32_e32 v81, 1.0, v81
	v_rcp_f32_e32 v78, v78
	v_rcp_f32_e32 v79, v79
	v_rcp_f32_e32 v80, v80
	v_rcp_f32_e32 v81, v81
	v_pk_mul_f32 v[22:23], v[22:23], v[78:79]
	v_pk_mul_f32 v[24:25], v[24:25], v[80:81]
	v_cvt_pk_bf16_f32 v22, v22, v23
	v_cvt_pk_bf16_f32 v23, v24, v25
	s_waitcnt vmcnt(29)
	v_lshlrev_b32_e32 v66, 16, v212
	v_and_b32_e32 v67, 0xffff0000, v212
	v_lshlrev_b32_e32 v68, 16, v213
	v_and_b32_e32 v69, 0xffff0000, v213
	v_mul_f32_e32 v70, 0xbfb8aa3b, v66
	v_mul_f32_e32 v71, 0xbfb8aa3b, v67
	v_mul_f32_e32 v72, 0xbfb8aa3b, v68
	v_mul_f32_e32 v73, 0xbfb8aa3b, v69
	v_exp_f32_e32 v70, v70
	v_exp_f32_e32 v71, v71
	v_exp_f32_e32 v72, v72
	v_exp_f32_e32 v73, v73
	v_pk_mul_f32 v[26:27], v[26:27], v[66:67]
	v_pk_mul_f32 v[28:29], v[28:29], v[68:69]
	v_add_f32_e32 v70, 1.0, v70
	v_add_f32_e32 v71, 1.0, v71
	v_add_f32_e32 v72, 1.0, v72
	v_add_f32_e32 v73, 1.0, v73
	v_rcp_f32_e32 v70, v70
	v_rcp_f32_e32 v71, v71
	v_rcp_f32_e32 v72, v72
	v_rcp_f32_e32 v73, v73
	v_pk_mul_f32 v[26:27], v[26:27], v[70:71]
	v_pk_mul_f32 v[28:29], v[28:29], v[72:73]
	v_cvt_pk_bf16_f32 v26, v26, v27
	v_cvt_pk_bf16_f32 v27, v28, v29
	s_waitcnt vmcnt(28)
	v_lshlrev_b32_e32 v74, 16, v214
	v_and_b32_e32 v75, 0xffff0000, v214
	v_lshlrev_b32_e32 v76, 16, v215
	v_and_b32_e32 v77, 0xffff0000, v215
	v_mul_f32_e32 v78, 0xbfb8aa3b, v74
	v_mul_f32_e32 v79, 0xbfb8aa3b, v75
	v_mul_f32_e32 v80, 0xbfb8aa3b, v76
	v_mul_f32_e32 v81, 0xbfb8aa3b, v77
	v_exp_f32_e32 v78, v78
	v_exp_f32_e32 v79, v79
	v_exp_f32_e32 v80, v80
	v_exp_f32_e32 v81, v81
	v_pk_mul_f32 v[30:31], v[30:31], v[74:75]
	v_pk_mul_f32 v[32:33], v[32:33], v[76:77]
	v_add_f32_e32 v78, 1.0, v78
	v_add_f32_e32 v79, 1.0, v79
	v_add_f32_e32 v80, 1.0, v80
	v_add_f32_e32 v81, 1.0, v81
	v_rcp_f32_e32 v78, v78
	v_rcp_f32_e32 v79, v79
	v_rcp_f32_e32 v80, v80
	v_rcp_f32_e32 v81, v81
	v_pk_mul_f32 v[30:31], v[30:31], v[78:79]
	v_pk_mul_f32 v[32:33], v[32:33], v[80:81]
	v_cvt_pk_bf16_f32 v30, v30, v31
	v_cvt_pk_bf16_f32 v31, v32, v33
	s_waitcnt vmcnt(27)
; DI unsigned pk2(float a, float b) { f32x2 v = {a, b}; bf16v2 r = __builtin_convertvector(v, bf16v2); return __builtin_bit_cast(unsigned, r); }
; DI float bf_lo(unsigned u) { return __uint_as_float(u << 16); }
; DI float bf_hi(unsigned u) { return __uint_as_float(u & 0xffff0000u); }
; DI float silu_mul(float o, float g) { return o * g * __builtin_amdgcn_rcpf(1.0f + __builtin_amdgcn_exp2f(g * -1.4426950408889634f)); }
; DI void attnB_item(bf16_t* z, int hh, int qs, LAS bf16_t* vs, int lane) {
;     ...
;         for (int dt = 0; dt < 4; ++dt)
; #pragma unroll
;             for (int g = 0; g < 4; ++g) {
;                 const int d0 = (dt << 9) | (g << 7);
;                 const u32x2 gv = *(const u32x2*)(grow + d0);
;                 u32x2 o; o.x = pk2(silu_mul(acc[dt][4 * g], bf_lo(gv.x)), silu_mul(acc[dt][4 * g + 1], bf_hi(gv.x)));
;                 o.y = pk2(silu_mul(acc[dt][4 * g + 2], bf_lo(gv.y)), silu_mul(acc[dt][4 * g + 3], bf_hi(gv.y)));
;                 *(u32x2*)(orow + d0) = o;
;             }
	v_lshlrev_b32_e32 v66, 16, v216
	v_and_b32_e32 v67, 0xffff0000, v216
	v_lshlrev_b32_e32 v68, 16, v217
	v_and_b32_e32 v69, 0xffff0000, v217
	v_mul_f32_e32 v70, 0xbfb8aa3b, v66
	v_mul_f32_e32 v71, 0xbfb8aa3b, v67
	v_mul_f32_e32 v72, 0xbfb8aa3b, v68
	v_mul_f32_e32 v73, 0xbfb8aa3b, v69
	v_exp_f32_e32 v70, v70
	v_exp_f32_e32 v71, v71
	v_exp_f32_e32 v72, v72
	v_exp_f32_e32 v73, v73
	v_pk_mul_f32 v[2:3], v[2:3], v[66:67]
	v_pk_mul_f32 v[4:5], v[4:5], v[68:69]
	v_add_f32_e32 v70, 1.0, v70
	v_add_f32_e32 v71, 1.0, v71
	v_add_f32_e32 v72, 1.0, v72
	v_add_f32_e32 v73, 1.0, v73
	v_rcp_f32_e32 v70, v70
	v_rcp_f32_e32 v71, v71
	v_rcp_f32_e32 v72, v72
	v_rcp_f32_e32 v73, v73
	v_pk_mul_f32 v[2:3], v[2:3], v[70:71]
	v_pk_mul_f32 v[4:5], v[4:5], v[72:73]
	v_cvt_pk_bf16_f32 v2, v2, v3
	v_cvt_pk_bf16_f32 v3, v4, v5
	s_waitcnt vmcnt(26)
	v_lshlrev_b32_e32 v74, 16, v218
	v_and_b32_e32 v75, 0xffff0000, v218
	v_lshlrev_b32_e32 v76, 16, v219
	v_and_b32_e32 v77, 0xffff0000, v219
	v_mul_f32_e32 v78, 0xbfb8aa3b, v74
	v_mul_f32_e32 v79, 0xbfb8aa3b, v75
	v_mul_f32_e32 v80, 0xbfb8aa3b, v76
	v_mul_f32_e32 v81, 0xbfb8aa3b, v77
	v_exp_f32_e32 v78, v78
	v_exp_f32_e32 v79, v79
	v_exp_f32_e32 v80, v80
	v_exp_f32_e32 v81, v81
	v_pk_mul_f32 v[6:7], v[6:7], v[74:75]
	v_pk_mul_f32 v[8:9], v[8:9], v[76:77]
	v_add_f32_e32 v78, 1.0, v78
	v_add_f32_e32 v79, 1.0, v79
	v_add_f32_e32 v80, 1.0, v80
	v_add_f32_e32 v81, 1.0, v81
	v_rcp_f32_e32 v78, v78
	v_rcp_f32_e32 v79, v79
	v_rcp_f32_e32 v80, v80
	v_rcp_f32_e32 v81, v81
	v_pk_mul_f32 v[6:7], v[6:7], v[78:79]
	v_pk_mul_f32 v[8:9], v[8:9], v[80:81]
	v_cvt_pk_bf16_f32 v6, v6, v7
	v_cvt_pk_bf16_f32 v7, v8, v9
	s_waitcnt vmcnt(25)
	v_lshlrev_b32_e32 v66, 16, v220
	v_and_b32_e32 v67, 0xffff0000, v220
	v_lshlrev_b32_e32 v68, 16, v221
	v_and_b32_e32 v69, 0xffff0000, v221
	v_mul_f32_e32 v70, 0xbfb8aa3b, v66
	v_mul_f32_e32 v71, 0xbfb8aa3b, v67
	v_mul_f32_e32 v72, 0xbfb8aa3b, v68
	v_mul_f32_e32 v73, 0xbfb8aa3b, v69
	v_exp_f32_e32 v70, v70
	v_exp_f32_e32 v71, v71
	v_exp_f32_e32 v72, v72
	v_exp_f32_e32 v73, v73
	v_pk_mul_f32 v[10:11], v[10:11], v[66:67]
	v_pk_mul_f32 v[12:13], v[12:13], v[68:69]
	v_add_f32_e32 v70, 1.0, v70
	v_add_f32_e32 v71, 1.0, v71
	v_add_f32_e32 v72, 1.0, v72
	v_add_f32_e32 v73, 1.0, v73
	v_rcp_f32_e32 v70, v70
	v_rcp_f32_e32 v71, v71
	v_rcp_f32_e32 v72, v72
	v_rcp_f32_e32 v73, v73
	v_pk_mul_f32 v[10:11], v[10:11], v[70:71]
	v_pk_mul_f32 v[12:13], v[12:13], v[72:73]
	v_cvt_pk_bf16_f32 v10, v10, v11
	v_cvt_pk_bf16_f32 v11, v12, v13
	s_waitcnt vmcnt(24)
	v_lshlrev_b32_e32 v74, 16, v222
	v_and_b32_e32 v75, 0xffff0000, v222
	v_lshlrev_b32_e32 v76, 16, v223
	v_and_b32_e32 v77, 0xffff0000, v223
	v_mul_f32_e32 v78, 0xbfb8aa3b, v74
	v_mul_f32_e32 v79, 0xbfb8aa3b, v75
	v_mul_f32_e32 v80, 0xbfb8aa3b, v76
	v_mul_f32_e32 v81, 0xbfb8aa3b, v77
	v_exp_f32_e32 v78, v78
	v_exp_f32_e32 v79, v79
	v_exp_f32_e32 v80, v80
	v_exp_f32_e32 v81, v81
	v_pk_mul_f32 v[14:15], v[14:15], v[74:75]
	v_pk_mul_f32 v[16:17], v[16:17], v[76:77]
	v_add_f32_e32 v78, 1.0, v78
	v_add_f32_e32 v79, 1.0, v79
	v_add_f32_e32 v80, 1.0, v80
	v_add_f32_e32 v81, 1.0, v81
	v_rcp_f32_e32 v78, v78
	v_rcp_f32_e32 v79, v79
	v_rcp_f32_e32 v80, v80
	v_rcp_f32_e32 v81, v81
	v_pk_mul_f32 v[14:15], v[14:15], v[78:79]
	v_pk_mul_f32 v[16:17], v[16:17], v[80:81]
	v_cvt_pk_bf16_f32 v14, v14, v15
	v_cvt_pk_bf16_f32 v15, v16, v17
	global_store_dwordx2 v[146:147], v[50:51], off
	global_store_dwordx2 v[146:147], v[54:55], off offset:256
	global_store_dwordx2 v[146:147], v[58:59], off offset:512
	global_store_dwordx2 v[146:147], v[62:63], off offset:768
	global_store_dwordx2 v[146:147], v[34:35], off offset:1024
	global_store_dwordx2 v[146:147], v[38:39], off offset:1280
	global_store_dwordx2 v[146:147], v[42:43], off offset:1536
	global_store_dwordx2 v[146:147], v[46:47], off offset:1792
	global_store_dwordx2 v[146:147], v[18:19], off offset:2048
	global_store_dwordx2 v[146:147], v[22:23], off offset:2304
	global_store_dwordx2 v[146:147], v[26:27], off offset:2560
	global_store_dwordx2 v[146:147], v[30:31], off offset:2816
	global_store_dwordx2 v[146:147], v[2:3], off offset:3072
	global_store_dwordx2 v[146:147], v[6:7], off offset:3328
	global_store_dwordx2 v[146:147], v[10:11], off offset:3584
	global_store_dwordx2 v[146:147], v[14:15], off offset:3840
	s_branch .LBB0_130
